# P7 fusion + MLA steady-loop pad cleanup + P9 start stagger (workgroups 128-255, which have one unit less, start ~11us late so epilogue store bursts of the two halves interleave)
# baseline (speedup 1.0000x reference)
.LBB0_889:
	ds_read_b128 v[2:5], v203 offset:16384
	s_waitcnt lgkmcnt(4)
	v_mfma_f32_32x32x16_bf16 v[112:127], v[168:171], v[160:163], v[48:63]
	v_exp_f32_e32 v68, v68
	v_exp_f32_e32 v69, v69
	v_exp_f32_e32 v70, v70
	ds_read_b128 v[6:9], v203 offset:24576
	s_waitcnt lgkmcnt(4)
	v_mfma_f32_32x32x16_bf16 v[96:111], v[172:175], v[160:163], v[48:63]
	v_exp_f32_e32 v71, v71
	v_exp_f32_e32 v72, v72
	v_exp_f32_e32 v73, v73
	ds_read_b128 v[10:13], v202 offset:16384
	s_waitcnt lgkmcnt(4)
	v_mfma_f32_32x32x16_bf16 v[112:127], v[180:183], v[156:159], v[112:127]
	v_exp_f32_e32 v74, v74
	v_exp_f32_e32 v75, v75
	v_exp_f32_e32 v76, v76
	ds_read_b128 v[168:171], v202 offset:24576
	s_waitcnt lgkmcnt(4)
	v_mfma_f32_32x32x16_bf16 v[96:111], v[176:179], v[156:159], v[96:111]
	v_exp_f32_e32 v77, v77
	v_exp_f32_e32 v78, v78
	v_exp_f32_e32 v79, v79
	ds_read_b128 v[172:175], v199 offset:16384
	v_add_f32_e32 v1, v80, v81
	s_waitcnt lgkmcnt(4)
	v_mfma_f32_32x32x16_bf16 v[112:127], v[2:5], v[152:155], v[112:127]
	v_add_f32_e32 v1, v82, v1
	v_add_f32_e32 v1, v83, v1
	v_add_f32_e32 v1, v84, v1
	v_add_f32_e32 v1, v85, v1
	v_cvt_pk_bf16_f32 v164, v80, v81
	v_cvt_pk_bf16_f32 v165, v82, v83
	ds_read_b128 v[2:5], v199 offset:24576
	s_waitcnt lgkmcnt(4)
	v_mfma_f32_32x32x16_bf16 v[96:111], v[6:9], v[152:155], v[96:111]
	v_add_f32_e32 v1, v86, v1
	v_add_f32_e32 v1, v87, v1
	v_add_f32_e32 v1, v88, v1
	v_add_f32_e32 v1, v89, v1
	v_cvt_pk_bf16_f32 v166, v84, v85
	v_cvt_pk_bf16_f32 v167, v86, v87
	ds_read_b128 v[6:9], v198 offset:16384
	s_waitcnt lgkmcnt(4)
	v_mfma_f32_32x32x16_bf16 v[112:127], v[10:13], v[148:151], v[112:127]
	v_add_f32_e32 v1, v90, v1
	v_add_f32_e32 v1, v91, v1
	v_add_f32_e32 v1, v92, v1
	v_add_f32_e32 v1, v93, v1
	v_cvt_pk_bf16_f32 v136, v88, v89
	v_cvt_pk_bf16_f32 v137, v90, v91
	ds_read_b128 v[10:13], v198 offset:24576
	s_waitcnt lgkmcnt(4)
	v_mfma_f32_32x32x16_bf16 v[96:111], v[168:171], v[148:151], v[96:111]
	v_add_f32_e32 v1, v94, v1
	v_add_f32_e32 v1, v95, v1
	v_add_f32_e32 v1, v64, v1
	v_add_f32_e32 v1, v65, v1
	v_cvt_pk_bf16_f32 v138, v92, v93
	v_cvt_pk_bf16_f32 v139, v94, v95
	s_waitcnt lgkmcnt(3)
	v_mfma_f32_32x32x16_bf16 v[112:127], v[172:175], v[144:147], v[112:127]
	v_add_f32_e32 v1, v66, v1
	v_add_f32_e32 v1, v67, v1
	v_add_f32_e32 v1, v68, v1
	v_add_f32_e32 v1, v69, v1
	v_cvt_pk_bf16_f32 v132, v64, v65
	v_cvt_pk_bf16_f32 v133, v66, v67
	s_waitcnt lgkmcnt(2)
	v_mfma_f32_32x32x16_bf16 v[96:111], v[2:5], v[144:147], v[96:111]
	v_add_f32_e32 v1, v70, v1
	v_add_f32_e32 v1, v71, v1
	v_add_f32_e32 v1, v72, v1
	v_add_f32_e32 v1, v73, v1
	v_cvt_pk_bf16_f32 v134, v68, v69
	v_cvt_pk_bf16_f32 v135, v70, v71
	ds_read_b64_tr_b16 v[2:3], v197
	ds_read_b64_tr_b16 v[4:5], v197 offset:512
	s_waitcnt lgkmcnt(3)
	v_mfma_f32_32x32x16_bf16 v[112:127], v[6:9], v[140:143], v[112:127]
	v_add_f32_e32 v1, v74, v1
	v_add_f32_e32 v1, v75, v1
	v_add_f32_e32 v1, v76, v1
	v_add_f32_e32 v1, v77, v1
	v_cvt_pk_bf16_f32 v128, v72, v73
	v_cvt_pk_bf16_f32 v129, v74, v75
	ds_read_b64_tr_b16 v[64:65], v197 offset:4096
	ds_read_b64_tr_b16 v[66:67], v197 offset:4608
	s_waitcnt lgkmcnt(4)
	v_mfma_f32_32x32x16_bf16 v[96:111], v[10:13], v[140:143], v[96:111]
	v_add_f32_e32 v1, v78, v1
	v_add_f32_e32 v1, v79, v1
	v_add_f32_e32 v1, 0, v1
	v_cvt_pk_bf16_f32 v130, v76, v77
	v_cvt_pk_bf16_f32 v131, v78, v79
	s_add_u32 s0, s6, 0xfffb8000
	s_addc_u32 s1, s7, -1
	s_mov_b32 m0, s81
	s_nop 0
	global_load_lds_dwordx4 v200, s[0:1]
	s_add_i32 s8, s81, 0x400
	s_mov_b32 m0, s8
	s_nop 0
	global_load_lds_dwordx4 v201, s[0:1]
	s_add_u32 s0, s4, 0xffff0000
	s_addc_u32 s1, s5, -1
	s_add_i32 s8, s74, 0x14000
	s_mov_b32 m0, s8
	s_nop 0
	global_load_lds_dwordx4 v204, s[0:1]
	ds_read_b64_tr_b16 v[6:7], v197 offset:1024
	ds_read_b64_tr_b16 v[8:9], v197 offset:1536
	ds_read_b64_tr_b16 v[10:11], v197 offset:5120
	ds_read_b64_tr_b16 v[12:13], v197 offset:5632
	v_add_f32_e32 v14, v216, v1
	v_max_f32_e32 v1, v113, v113
	v_max_f32_e32 v15, v112, v112
	v_max_f32_e32 v1, v15, v1
	v_max3_f32 v15, v114, v115, v97
	v_max3_f32 v1, v1, v96, v98
	v_max3_f32 v1, v1, v99, v116
	s_waitcnt lgkmcnt(6)
	v_mfma_f32_32x32x16_bf16 v[32:47], v[164:167], v[2:5], v[32:47]
	v_max3_f32 v2, v15, v118, v119
	v_max3_f32 v1, v1, v117, v100
	v_max3_f32 v2, v2, v102, v103
	v_max3_f32 v1, v1, v101, v120
	v_max3_f32 v2, v2, v122, v123
	v_max3_f32 v1, v1, v121, v104
	v_max3_f32 v2, v2, v106, v107
	s_waitcnt lgkmcnt(4)
	v_mfma_f32_32x32x16_bf16 v[16:31], v[164:167], v[64:67], v[16:31]
	v_max3_f32 v1, v1, v105, v124
	v_max3_f32 v2, v2, v126, v127
	v_max3_f32 v1, v1, v125, v108
	v_max3_f32 v2, v2, v110, v111
	v_max3_f32 v1, v1, v109, v2
	v_cmp_lt_f32_e32 vcc, s85, v1
	s_cmp_lg_u64 vcc, 0
	s_cselect_b64 s[0:1], -1, 0
	s_cbranch_vccnz .LBB0_901
.LBB0_890:
	s_waitcnt lgkmcnt(2)
	v_mfma_f32_32x32x16_bf16 v[32:47], v[136:139], v[6:9], v[32:47]
	ds_read_b64_tr_b16 v[66:67], v197 offset:2560
	ds_read_b64_tr_b16 v[64:65], v197 offset:2048
	ds_read_b128 v[2:5], v206 offset:32768
	v_exp_f32_e32 v112, v112
	v_exp_f32_e32 v113, v113
	v_exp_f32_e32 v114, v114
	v_exp_f32_e32 v115, v115
	s_waitcnt lgkmcnt(3)
	v_mfma_f32_32x32x16_bf16 v[16:31], v[136:139], v[10:13], v[16:31]
	ds_read_b64_tr_b16 v[70:71], v197 offset:6656
	ds_read_b64_tr_b16 v[68:69], v197 offset:6144
	ds_read_b128 v[6:9], v206 offset:40960
	v_exp_f32_e32 v116, v116
	v_exp_f32_e32 v117, v117
	v_exp_f32_e32 v118, v118
	v_exp_f32_e32 v119, v119
	s_waitcnt lgkmcnt(4)
	v_mfma_f32_32x32x16_bf16 v[32:47], v[132:135], v[64:67], v[32:47]
	ds_read_b64_tr_b16 v[74:75], v197 offset:3584
	ds_read_b64_tr_b16 v[72:73], v197 offset:3072
	ds_read_b128 v[10:13], v208 offset:32768
	v_exp_f32_e32 v120, v120
	v_exp_f32_e32 v121, v121
	v_exp_f32_e32 v122, v122
	s_waitcnt lgkmcnt(4)
	v_mfma_f32_32x32x16_bf16 v[16:31], v[132:135], v[68:71], v[16:31]
	ds_read_b64_tr_b16 v[66:67], v197 offset:7680
	ds_read_b64_tr_b16 v[64:65], v197 offset:7168
	ds_read_b128 v[168:171], v208 offset:40960
	v_exp_f32_e32 v123, v123
	v_exp_f32_e32 v124, v124
	v_exp_f32_e32 v125, v125
	s_waitcnt lgkmcnt(4)
	v_mfma_f32_32x32x16_bf16 v[32:47], v[128:131], v[72:75], v[32:47]
	v_exp_f32_e32 v126, v126
	v_exp_f32_e32 v127, v127
	v_exp_f32_e32 v96, v96
	s_waitcnt lgkmcnt(1)
	v_mfma_f32_32x32x16_bf16 v[16:31], v[128:131], v[64:67], v[16:31]
	v_exp_f32_e32 v97, v97
	v_exp_f32_e32 v98, v98
	v_exp_f32_e32 v99, v99
	s_waitcnt vmcnt(3) lgkmcnt(0)
	s_barrier
	s_andn2_b64 vcc, exec, s[0:1]
	v_add_u32_e32 v1, s78, v186
	s_cbranch_vccnz .LBB0_892
	ds_read_b128 v[64:67], v1 offset:96
	ds_read_b128 v[68:71], v1 offset:64
	ds_read_b128 v[72:75], v1 offset:32
	ds_read_b128 v[76:79], v1
	s_waitcnt lgkmcnt(3)
	v_pk_mul_f32 v[44:45], v[44:45], v[64:65]
	s_waitcnt lgkmcnt(2)
	v_pk_mul_f32 v[40:41], v[40:41], v[68:69]
	s_waitcnt lgkmcnt(1)
	v_pk_mul_f32 v[36:37], v[36:37], v[72:73]
	v_pk_mul_f32 v[46:47], v[46:47], v[66:67]
	v_pk_mul_f32 v[42:43], v[42:43], v[70:71]
	v_pk_mul_f32 v[38:39], v[38:39], v[74:75]
	s_waitcnt lgkmcnt(0)
	v_pk_mul_f32 v[34:35], v[34:35], v[78:79]
	v_pk_mul_f32 v[32:33], v[32:33], v[76:77]
	v_pk_mul_f32 v[28:29], v[28:29], v[64:65]
	v_pk_mul_f32 v[24:25], v[24:25], v[68:69]
	v_pk_mul_f32 v[20:21], v[20:21], v[72:73]
	v_pk_mul_f32 v[30:31], v[30:31], v[66:67]
	v_pk_mul_f32 v[26:27], v[26:27], v[70:71]
	v_pk_mul_f32 v[22:23], v[22:23], v[74:75]
	v_pk_mul_f32 v[18:19], v[18:19], v[78:79]
	v_pk_mul_f32 v[16:17], v[16:17], v[76:77]
.LBB0_892:
	ds_read_b128 v[172:175], v203 offset:32768
	v_mfma_f32_32x32x16_bf16 v[80:95], v[2:5], v[160:163], v[48:63]
	v_exp_f32_e32 v100, v100
	v_exp_f32_e32 v101, v101
	v_exp_f32_e32 v102, v102
	ds_read_b128 v[2:5], v203 offset:40960
	v_mfma_f32_32x32x16_bf16 v[64:79], v[6:9], v[160:163], v[48:63]
	v_exp_f32_e32 v103, v103
	v_exp_f32_e32 v104, v104
	v_exp_f32_e32 v105, v105
	ds_read_b128 v[6:9], v202 offset:32768
	v_mfma_f32_32x32x16_bf16 v[80:95], v[10:13], v[156:159], v[80:95]
	v_exp_f32_e32 v106, v106
	v_exp_f32_e32 v107, v107
	v_exp_f32_e32 v108, v108
	ds_read_b128 v[10:13], v202 offset:40960
	s_waitcnt lgkmcnt(4)
	v_mfma_f32_32x32x16_bf16 v[64:79], v[168:171], v[156:159], v[64:79]
	v_exp_f32_e32 v109, v109
	v_exp_f32_e32 v110, v110
	v_exp_f32_e32 v111, v111
	ds_read_b128 v[168:171], v199 offset:32768
	v_add_f32_e32 v15, v112, v113
	s_waitcnt lgkmcnt(4)
	v_mfma_f32_32x32x16_bf16 v[80:95], v[172:175], v[152:155], v[80:95]
	v_add_f32_e32 v15, v114, v15
	v_add_f32_e32 v15, v115, v15
	v_add_f32_e32 v15, v116, v15
	v_add_f32_e32 v15, v117, v15
	v_cvt_pk_bf16_f32 v164, v112, v113
	v_cvt_pk_bf16_f32 v165, v114, v115
	ds_read_b128 v[112:115], v199 offset:40960
	s_waitcnt lgkmcnt(4)
	v_mfma_f32_32x32x16_bf16 v[64:79], v[2:5], v[152:155], v[64:79]
	v_add_f32_e32 v15, v118, v15
	v_add_f32_e32 v15, v119, v15
	v_add_f32_e32 v15, v120, v15
	v_add_f32_e32 v15, v121, v15
	v_cvt_pk_bf16_f32 v166, v116, v117
	v_cvt_pk_bf16_f32 v167, v118, v119
	ds_read_b128 v[2:5], v198 offset:32768
	s_waitcnt lgkmcnt(4)
	v_mfma_f32_32x32x16_bf16 v[80:95], v[6:9], v[148:151], v[80:95]
	v_add_f32_e32 v15, v122, v15
	v_add_f32_e32 v15, v123, v15
	v_add_f32_e32 v15, v124, v15
	v_add_f32_e32 v15, v125, v15
	v_cvt_pk_bf16_f32 v136, v120, v121
	v_cvt_pk_bf16_f32 v137, v122, v123
	ds_read_b128 v[6:9], v198 offset:40960
	s_waitcnt lgkmcnt(4)
	v_mfma_f32_32x32x16_bf16 v[64:79], v[10:13], v[148:151], v[64:79]
	v_add_f32_e32 v15, v126, v15
	v_add_f32_e32 v15, v127, v15
	v_add_f32_e32 v15, v96, v15
	v_add_f32_e32 v15, v97, v15
	v_cvt_pk_bf16_f32 v138, v124, v125
	v_cvt_pk_bf16_f32 v139, v126, v127
	s_waitcnt lgkmcnt(3)
	v_mfma_f32_32x32x16_bf16 v[80:95], v[168:171], v[144:147], v[80:95]
	v_add_f32_e32 v10, v98, v15
	v_add_f32_e32 v10, v99, v10
	v_add_f32_e32 v10, v100, v10
	v_add_f32_e32 v10, v101, v10
	v_cvt_pk_bf16_f32 v132, v96, v97
	v_cvt_pk_bf16_f32 v133, v98, v99
	s_waitcnt lgkmcnt(2)
	v_mfma_f32_32x32x16_bf16 v[64:79], v[112:115], v[144:147], v[64:79]
	v_add_f32_e32 v10, v102, v10
	v_add_f32_e32 v10, v103, v10
	v_add_f32_e32 v10, v104, v10
	v_add_f32_e32 v10, v105, v10
	v_cvt_pk_bf16_f32 v134, v100, v101
	v_cvt_pk_bf16_f32 v135, v102, v103
	ds_read_b64_tr_b16 v[96:97], v197 offset:8192
	ds_read_b64_tr_b16 v[98:99], v197 offset:8704
	s_waitcnt lgkmcnt(3)
	v_mfma_f32_32x32x16_bf16 v[80:95], v[2:5], v[140:143], v[80:95]
	v_add_f32_e32 v10, v106, v10
	v_add_f32_e32 v10, v107, v10
	v_add_f32_e32 v10, v108, v10
	v_add_f32_e32 v10, v109, v10
	v_cvt_pk_bf16_f32 v128, v104, v105
	v_cvt_pk_bf16_f32 v129, v106, v107
	ds_read_b64_tr_b16 v[2:3], v197 offset:12288
	ds_read_b64_tr_b16 v[4:5], v197 offset:12800
	s_waitcnt lgkmcnt(4)
	v_mfma_f32_32x32x16_bf16 v[64:79], v[6:9], v[140:143], v[64:79]
	v_add_f32_e32 v10, v110, v10
	v_add_f32_e32 v10, v111, v10
	v_add_f32_e32 v15, 0, v10
	v_cvt_pk_bf16_f32 v130, v108, v109
	v_cvt_pk_bf16_f32 v131, v110, v111
	s_add_u32 s0, s6, 0xfffd0000
	s_addc_u32 s1, s7, -1
	s_mov_b32 m0, s79
	s_nop 0
	global_load_lds_dwordx4 v200, s[0:1]
	s_add_i32 s8, s79, 0x400
	s_mov_b32 m0, s8
	s_nop 0
	global_load_lds_dwordx4 v201, s[0:1]
	s_add_i32 s0, s74, 0x16000
	s_mov_b32 m0, s0
	s_nop 0
	global_load_lds_dwordx4 v204, s[4:5]
	ds_read_b64_tr_b16 v[6:7], v197 offset:9216
	ds_read_b64_tr_b16 v[8:9], v197 offset:9728
	ds_read_b64_tr_b16 v[10:11], v197 offset:13312
	ds_read_b64_tr_b16 v[12:13], v197 offset:13824
	v_add_f32_e32 v14, v14, v15
	v_max_f32_e32 v15, v81, v81
	v_max_f32_e32 v100, v80, v80
	v_max_f32_e32 v15, v100, v15
	v_max3_f32 v100, v82, v83, v65
	v_max3_f32 v15, v15, v64, v66
	v_max3_f32 v15, v15, v67, v84
	s_waitcnt lgkmcnt(6)
	v_mfma_f32_32x32x16_bf16 v[32:47], v[164:167], v[96:99], v[32:47]
	v_max3_f32 v96, v100, v86, v87
	v_max3_f32 v15, v15, v85, v68
	v_max3_f32 v96, v96, v70, v71
	v_max3_f32 v15, v15, v69, v88
	v_max3_f32 v96, v96, v90, v91
	v_max3_f32 v15, v15, v89, v72
	v_max3_f32 v96, v96, v74, v75
	s_waitcnt lgkmcnt(4)
	v_mfma_f32_32x32x16_bf16 v[16:31], v[164:167], v[2:5], v[16:31]
	v_max3_f32 v2, v15, v73, v92
	v_max3_f32 v3, v96, v94, v95
	v_max3_f32 v2, v2, v93, v76
	v_max3_f32 v3, v3, v78, v79
	v_max3_f32 v2, v2, v77, v3
	v_cmp_lt_f32_e32 vcc, s85, v2
	s_cmp_lg_u64 vcc, 0
	s_cselect_b64 s[0:1], -1, 0
	s_cbranch_vccnz .LBB0_904
.LBB0_893:
	s_waitcnt lgkmcnt(2)
	v_mfma_f32_32x32x16_bf16 v[32:47], v[136:139], v[6:9], v[32:47]
	ds_read_b64_tr_b16 v[98:99], v197 offset:10752
	ds_read_b64_tr_b16 v[96:97], v197 offset:10240
	ds_read_b128 v[2:5], v206 offset:49152
	v_exp_f32_e32 v80, v80
	v_exp_f32_e32 v81, v81
	v_exp_f32_e32 v82, v82
	v_exp_f32_e32 v83, v83
	s_waitcnt lgkmcnt(3)
	v_mfma_f32_32x32x16_bf16 v[16:31], v[136:139], v[10:13], v[16:31]
	ds_read_b64_tr_b16 v[102:103], v197 offset:14848
	ds_read_b64_tr_b16 v[100:101], v197 offset:14336
	ds_read_b128 v[6:9], v206 offset:57344
	v_exp_f32_e32 v84, v84
	v_exp_f32_e32 v85, v85
	v_exp_f32_e32 v86, v86
	v_exp_f32_e32 v87, v87
	s_waitcnt lgkmcnt(4)
	v_mfma_f32_32x32x16_bf16 v[32:47], v[132:135], v[96:99], v[32:47]
	ds_read_b64_tr_b16 v[106:107], v197 offset:11776
	ds_read_b64_tr_b16 v[104:105], v197 offset:11264
	ds_read_b128 v[10:13], v208 offset:49152
	v_exp_f32_e32 v88, v88
	v_exp_f32_e32 v89, v89
	v_exp_f32_e32 v90, v90
	s_waitcnt lgkmcnt(4)
	v_mfma_f32_32x32x16_bf16 v[16:31], v[132:135], v[100:103], v[16:31]
	ds_read_b64_tr_b16 v[98:99], v197 offset:15872
	ds_read_b64_tr_b16 v[96:97], v197 offset:15360
	ds_read_b128 v[168:171], v208 offset:57344
	v_exp_f32_e32 v91, v91
	v_exp_f32_e32 v92, v92
	v_exp_f32_e32 v93, v93
	s_waitcnt lgkmcnt(4)
	v_mfma_f32_32x32x16_bf16 v[32:47], v[128:131], v[104:107], v[32:47]
	v_exp_f32_e32 v94, v94
	v_exp_f32_e32 v95, v95
	v_exp_f32_e32 v64, v64
	s_waitcnt lgkmcnt(1)
	v_mfma_f32_32x32x16_bf16 v[16:31], v[128:131], v[96:99], v[16:31]
	v_exp_f32_e32 v65, v65
	v_exp_f32_e32 v66, v66
	v_exp_f32_e32 v67, v67
	s_waitcnt vmcnt(3) lgkmcnt(0)
	s_barrier
	s_andn2_b64 vcc, exec, s[0:1]
	s_cbranch_vccnz .LBB0_895
	ds_read_b128 v[96:99], v1 offset:96
	ds_read_b128 v[100:103], v1 offset:64
	ds_read_b128 v[104:107], v1 offset:32
	ds_read_b128 v[108:111], v1
	s_waitcnt lgkmcnt(3)
	v_pk_mul_f32 v[44:45], v[44:45], v[96:97]
	s_waitcnt lgkmcnt(2)
	v_pk_mul_f32 v[40:41], v[40:41], v[100:101]
	s_waitcnt lgkmcnt(1)
	v_pk_mul_f32 v[36:37], v[36:37], v[104:105]
	v_pk_mul_f32 v[46:47], v[46:47], v[98:99]
	v_pk_mul_f32 v[42:43], v[42:43], v[102:103]
	v_pk_mul_f32 v[38:39], v[38:39], v[106:107]
	s_waitcnt lgkmcnt(0)
	v_pk_mul_f32 v[34:35], v[34:35], v[110:111]
	v_pk_mul_f32 v[32:33], v[32:33], v[108:109]
	v_pk_mul_f32 v[28:29], v[28:29], v[96:97]
	v_pk_mul_f32 v[24:25], v[24:25], v[100:101]
	v_pk_mul_f32 v[20:21], v[20:21], v[104:105]
	v_pk_mul_f32 v[30:31], v[30:31], v[98:99]
	v_pk_mul_f32 v[26:27], v[26:27], v[102:103]
	v_pk_mul_f32 v[22:23], v[22:23], v[106:107]
	v_pk_mul_f32 v[18:19], v[18:19], v[110:111]
	v_pk_mul_f32 v[16:17], v[16:17], v[108:109]
.LBB0_895:
	ds_read_b128 v[172:175], v203 offset:49152
	v_mfma_f32_32x32x16_bf16 v[112:127], v[2:5], v[160:163], v[48:63]
	v_exp_f32_e32 v68, v68
	v_exp_f32_e32 v69, v69
	v_exp_f32_e32 v70, v70
	ds_read_b128 v[2:5], v203 offset:57344
	v_mfma_f32_32x32x16_bf16 v[96:111], v[6:9], v[160:163], v[48:63]
	v_exp_f32_e32 v71, v71
	v_exp_f32_e32 v72, v72
	v_exp_f32_e32 v73, v73
	ds_read_b128 v[6:9], v202 offset:49152
	v_mfma_f32_32x32x16_bf16 v[112:127], v[10:13], v[156:159], v[112:127]
	v_exp_f32_e32 v74, v74
	v_exp_f32_e32 v75, v75
	v_exp_f32_e32 v76, v76
	ds_read_b128 v[10:13], v202 offset:57344
	s_waitcnt lgkmcnt(4)
	v_mfma_f32_32x32x16_bf16 v[96:111], v[168:171], v[156:159], v[96:111]
	v_exp_f32_e32 v77, v77
	v_exp_f32_e32 v78, v78
	v_exp_f32_e32 v79, v79
	ds_read_b128 v[168:171], v199 offset:49152
	v_add_f32_e32 v15, v80, v81
	s_waitcnt lgkmcnt(4)
	v_mfma_f32_32x32x16_bf16 v[112:127], v[172:175], v[152:155], v[112:127]
	v_add_f32_e32 v15, v82, v15
	v_add_f32_e32 v15, v83, v15
	v_add_f32_e32 v15, v84, v15
	v_add_f32_e32 v15, v85, v15
	v_cvt_pk_bf16_f32 v164, v80, v81
	v_cvt_pk_bf16_f32 v165, v82, v83
	ds_read_b128 v[80:83], v199 offset:57344
	s_waitcnt lgkmcnt(4)
	v_mfma_f32_32x32x16_bf16 v[96:111], v[2:5], v[152:155], v[96:111]
	v_add_f32_e32 v15, v86, v15
	v_add_f32_e32 v15, v87, v15
	v_add_f32_e32 v15, v88, v15
	v_add_f32_e32 v15, v89, v15
	v_cvt_pk_bf16_f32 v166, v84, v85
	v_cvt_pk_bf16_f32 v167, v86, v87
	ds_read_b128 v[2:5], v198 offset:49152
	s_waitcnt lgkmcnt(4)
	v_mfma_f32_32x32x16_bf16 v[112:127], v[6:9], v[148:151], v[112:127]
	v_add_f32_e32 v15, v90, v15
	v_add_f32_e32 v15, v91, v15
	v_add_f32_e32 v15, v92, v15
	v_add_f32_e32 v15, v93, v15
	v_cvt_pk_bf16_f32 v136, v88, v89
	v_cvt_pk_bf16_f32 v137, v90, v91
	ds_read_b128 v[6:9], v198 offset:57344
	s_waitcnt lgkmcnt(4)
	v_mfma_f32_32x32x16_bf16 v[96:111], v[10:13], v[148:151], v[96:111]
	v_add_f32_e32 v15, v94, v15
	v_add_f32_e32 v15, v95, v15
	v_add_f32_e32 v15, v64, v15
	v_add_f32_e32 v15, v65, v15
	v_cvt_pk_bf16_f32 v138, v92, v93
	v_cvt_pk_bf16_f32 v139, v94, v95
	s_waitcnt lgkmcnt(3)
	v_mfma_f32_32x32x16_bf16 v[112:127], v[168:171], v[144:147], v[112:127]
	v_add_f32_e32 v10, v66, v15
	v_add_f32_e32 v10, v67, v10
	v_add_f32_e32 v10, v68, v10
	v_add_f32_e32 v10, v69, v10
	v_cvt_pk_bf16_f32 v132, v64, v65
	v_cvt_pk_bf16_f32 v133, v66, v67
	s_waitcnt lgkmcnt(2)
	v_mfma_f32_32x32x16_bf16 v[96:111], v[80:83], v[144:147], v[96:111]
	v_add_f32_e32 v10, v70, v10
	v_add_f32_e32 v10, v71, v10
	v_add_f32_e32 v10, v72, v10
	v_add_f32_e32 v10, v73, v10
	v_cvt_pk_bf16_f32 v134, v68, v69
	v_cvt_pk_bf16_f32 v135, v70, v71
	ds_read_b64_tr_b16 v[64:65], v197 offset:16384
	ds_read_b64_tr_b16 v[66:67], v197 offset:16896
	s_waitcnt lgkmcnt(3)
	v_mfma_f32_32x32x16_bf16 v[112:127], v[2:5], v[140:143], v[112:127]
	v_add_f32_e32 v10, v74, v10
	v_add_f32_e32 v10, v75, v10
	v_add_f32_e32 v10, v76, v10
	v_add_f32_e32 v10, v77, v10
	v_cvt_pk_bf16_f32 v128, v72, v73
	v_cvt_pk_bf16_f32 v129, v74, v75
	ds_read_b64_tr_b16 v[2:3], v197 offset:20480
	ds_read_b64_tr_b16 v[4:5], v197 offset:20992
	s_waitcnt lgkmcnt(4)
	v_mfma_f32_32x32x16_bf16 v[96:111], v[6:9], v[140:143], v[96:111]
	v_add_f32_e32 v10, v78, v10
	v_add_f32_e32 v10, v79, v10
	v_add_f32_e32 v15, 0, v10
	v_cvt_pk_bf16_f32 v130, v76, v77
	v_cvt_pk_bf16_f32 v131, v78, v79
	s_add_u32 s0, s6, 0xfffe8000
	s_addc_u32 s1, s7, -1
	s_mov_b32 m0, s80
	s_nop 0
	global_load_lds_dwordx4 v200, s[0:1]
	s_add_i32 s8, s80, 0x400
	s_mov_b32 m0, s8
	s_nop 0
	global_load_lds_dwordx4 v201, s[0:1]
	s_add_u32 s0, s4, 0x10000
	s_addc_u32 s1, s5, 0
	s_mov_b32 m0, s75
	s_nop 0
	global_load_lds_dwordx4 v204, s[0:1]
	ds_read_b64_tr_b16 v[6:7], v197 offset:17408
	ds_read_b64_tr_b16 v[8:9], v197 offset:17920
	ds_read_b64_tr_b16 v[10:11], v197 offset:21504
	ds_read_b64_tr_b16 v[12:13], v197 offset:22016
	v_add_f32_e32 v14, v14, v15
	v_max_f32_e32 v15, v113, v113
	v_max_f32_e32 v68, v112, v112
	v_max_f32_e32 v15, v68, v15
	v_max3_f32 v68, v114, v115, v97
	v_max3_f32 v15, v15, v96, v98
	v_max3_f32 v15, v15, v99, v116
	s_waitcnt lgkmcnt(6)
	v_mfma_f32_32x32x16_bf16 v[32:47], v[164:167], v[64:67], v[32:47]
	v_max3_f32 v64, v68, v118, v119
	v_max3_f32 v15, v15, v117, v100
	v_max3_f32 v64, v64, v102, v103
	v_max3_f32 v15, v15, v101, v120
	v_max3_f32 v64, v64, v122, v123
	v_max3_f32 v15, v15, v121, v104
	v_max3_f32 v64, v64, v106, v107
	s_waitcnt lgkmcnt(4)
	v_mfma_f32_32x32x16_bf16 v[16:31], v[164:167], v[2:5], v[16:31]
	v_max3_f32 v2, v15, v105, v124
	v_max3_f32 v3, v64, v126, v127
	v_max3_f32 v2, v2, v125, v108
	v_max3_f32 v3, v3, v110, v111
	v_max3_f32 v2, v2, v109, v3
	v_cmp_lt_f32_e32 vcc, s85, v2
	s_cmp_lg_u64 vcc, 0
	s_cselect_b64 s[0:1], -1, 0
	s_cbranch_vccnz .LBB0_907
.LBB0_896:
	s_waitcnt lgkmcnt(2)
	v_mfma_f32_32x32x16_bf16 v[32:47], v[136:139], v[6:9], v[32:47]
	ds_read_b64_tr_b16 v[66:67], v197 offset:18944
	ds_read_b64_tr_b16 v[64:65], v197 offset:18432
	ds_read_b128 v[2:5], v206
	v_exp_f32_e32 v112, v112
	v_exp_f32_e32 v113, v113
	v_exp_f32_e32 v114, v114
	v_exp_f32_e32 v115, v115
	s_waitcnt lgkmcnt(3)
	v_mfma_f32_32x32x16_bf16 v[16:31], v[136:139], v[10:13], v[16:31]
	ds_read_b64_tr_b16 v[70:71], v197 offset:23040
	ds_read_b64_tr_b16 v[68:69], v197 offset:22528
	ds_read_b128 v[6:9], v206 offset:8192
	v_exp_f32_e32 v116, v116
	v_exp_f32_e32 v117, v117
	v_exp_f32_e32 v118, v118
	v_exp_f32_e32 v119, v119
	s_waitcnt lgkmcnt(4)
	v_mfma_f32_32x32x16_bf16 v[32:47], v[132:135], v[64:67], v[32:47]
	ds_read_b64_tr_b16 v[74:75], v197 offset:19968
	ds_read_b64_tr_b16 v[72:73], v197 offset:19456
	ds_read_b128 v[10:13], v208
	v_exp_f32_e32 v120, v120
	v_exp_f32_e32 v121, v121
	v_exp_f32_e32 v122, v122
	s_waitcnt lgkmcnt(4)
	v_mfma_f32_32x32x16_bf16 v[16:31], v[132:135], v[68:71], v[16:31]
	ds_read_b64_tr_b16 v[66:67], v197 offset:24064
	ds_read_b64_tr_b16 v[64:65], v197 offset:23552
	ds_read_b128 v[168:171], v208 offset:8192
	v_exp_f32_e32 v123, v123
	v_exp_f32_e32 v124, v124
	v_exp_f32_e32 v125, v125
	s_waitcnt lgkmcnt(4)
	v_mfma_f32_32x32x16_bf16 v[32:47], v[128:131], v[72:75], v[32:47]
	v_exp_f32_e32 v126, v126
	v_exp_f32_e32 v127, v127
	v_exp_f32_e32 v96, v96
	s_waitcnt lgkmcnt(1)
	v_mfma_f32_32x32x16_bf16 v[16:31], v[128:131], v[64:67], v[16:31]
	v_exp_f32_e32 v97, v97
	v_exp_f32_e32 v98, v98
	v_exp_f32_e32 v99, v99
	s_waitcnt vmcnt(3) lgkmcnt(0)
	s_barrier
	s_andn2_b64 vcc, exec, s[0:1]
	s_cbranch_vccnz .LBB0_898
	ds_read_b128 v[64:67], v1 offset:96
	ds_read_b128 v[68:71], v1 offset:64
	ds_read_b128 v[72:75], v1 offset:32
	ds_read_b128 v[76:79], v1
	s_waitcnt lgkmcnt(3)
	v_pk_mul_f32 v[44:45], v[44:45], v[64:65]
	s_waitcnt lgkmcnt(2)
	v_pk_mul_f32 v[40:41], v[40:41], v[68:69]
	s_waitcnt lgkmcnt(1)
	v_pk_mul_f32 v[36:37], v[36:37], v[72:73]
	v_pk_mul_f32 v[46:47], v[46:47], v[66:67]
	v_pk_mul_f32 v[42:43], v[42:43], v[70:71]
	v_pk_mul_f32 v[38:39], v[38:39], v[74:75]
	s_waitcnt lgkmcnt(0)
	v_pk_mul_f32 v[34:35], v[34:35], v[78:79]
	v_pk_mul_f32 v[32:33], v[32:33], v[76:77]
	v_pk_mul_f32 v[28:29], v[28:29], v[64:65]
	v_pk_mul_f32 v[24:25], v[24:25], v[68:69]
	v_pk_mul_f32 v[20:21], v[20:21], v[72:73]
	v_pk_mul_f32 v[30:31], v[30:31], v[66:67]
	v_pk_mul_f32 v[26:27], v[26:27], v[70:71]
	v_pk_mul_f32 v[22:23], v[22:23], v[74:75]
	v_pk_mul_f32 v[18:19], v[18:19], v[78:79]
	v_pk_mul_f32 v[16:17], v[16:17], v[76:77]
.LBB0_898:
	ds_read_b128 v[172:175], v203
	v_mfma_f32_32x32x16_bf16 v[80:95], v[2:5], v[160:163], v[48:63]
	v_exp_f32_e32 v100, v100
	v_exp_f32_e32 v101, v101
	v_exp_f32_e32 v102, v102
	ds_read_b128 v[2:5], v203 offset:8192
	v_mfma_f32_32x32x16_bf16 v[64:79], v[6:9], v[160:163], v[48:63]
	v_exp_f32_e32 v103, v103
	v_exp_f32_e32 v104, v104
	v_exp_f32_e32 v105, v105
	ds_read_b128 v[6:9], v202
	v_mfma_f32_32x32x16_bf16 v[80:95], v[10:13], v[156:159], v[80:95]
	v_exp_f32_e32 v106, v106
	v_exp_f32_e32 v107, v107
	v_exp_f32_e32 v108, v108
	ds_read_b128 v[10:13], v202 offset:8192
	s_waitcnt lgkmcnt(4)
	v_mfma_f32_32x32x16_bf16 v[64:79], v[168:171], v[156:159], v[64:79]
	v_exp_f32_e32 v109, v109
	v_exp_f32_e32 v110, v110
	v_exp_f32_e32 v111, v111
	ds_read_b128 v[168:171], v199
	v_add_f32_e32 v15, v112, v113
	s_waitcnt lgkmcnt(4)
	v_mfma_f32_32x32x16_bf16 v[80:95], v[172:175], v[152:155], v[80:95]
	v_add_f32_e32 v15, v114, v15
	v_add_f32_e32 v15, v115, v15
	v_add_f32_e32 v15, v116, v15
	v_add_f32_e32 v15, v117, v15
	v_cvt_pk_bf16_f32 v164, v112, v113
	v_cvt_pk_bf16_f32 v165, v114, v115
	ds_read_b128 v[112:115], v199 offset:8192
	s_waitcnt lgkmcnt(4)
	v_mfma_f32_32x32x16_bf16 v[64:79], v[2:5], v[152:155], v[64:79]
	v_add_f32_e32 v15, v118, v15
	v_add_f32_e32 v15, v119, v15
	v_add_f32_e32 v15, v120, v15
	v_add_f32_e32 v15, v121, v15
	v_cvt_pk_bf16_f32 v166, v116, v117
	v_cvt_pk_bf16_f32 v167, v118, v119
	ds_read_b128 v[2:5], v198
	s_waitcnt lgkmcnt(4)
	v_mfma_f32_32x32x16_bf16 v[80:95], v[6:9], v[148:151], v[80:95]
	v_add_f32_e32 v15, v122, v15
	v_add_f32_e32 v15, v123, v15
	v_add_f32_e32 v15, v124, v15
	v_add_f32_e32 v15, v125, v15
	v_cvt_pk_bf16_f32 v136, v120, v121
	v_cvt_pk_bf16_f32 v137, v122, v123
	ds_read_b128 v[6:9], v198 offset:8192
	s_waitcnt lgkmcnt(4)
	v_mfma_f32_32x32x16_bf16 v[64:79], v[10:13], v[148:151], v[64:79]
	v_add_f32_e32 v15, v126, v15
	v_add_f32_e32 v15, v127, v15
	v_add_f32_e32 v15, v96, v15
	v_add_f32_e32 v15, v97, v15
	v_cvt_pk_bf16_f32 v138, v124, v125
	v_cvt_pk_bf16_f32 v139, v126, v127
	s_waitcnt lgkmcnt(3)
	v_mfma_f32_32x32x16_bf16 v[80:95], v[168:171], v[144:147], v[80:95]
	v_add_f32_e32 v10, v98, v15
	v_add_f32_e32 v10, v99, v10
	v_add_f32_e32 v10, v100, v10
	v_add_f32_e32 v10, v101, v10
	v_cvt_pk_bf16_f32 v132, v96, v97
	v_cvt_pk_bf16_f32 v133, v98, v99
	s_waitcnt lgkmcnt(2)
	v_mfma_f32_32x32x16_bf16 v[64:79], v[112:115], v[144:147], v[64:79]
	v_add_f32_e32 v10, v102, v10
	v_add_f32_e32 v10, v103, v10
	v_add_f32_e32 v10, v104, v10
	v_add_f32_e32 v15, v105, v10
	v_cvt_pk_bf16_f32 v134, v100, v101
	v_cvt_pk_bf16_f32 v135, v102, v103
	ds_read_b64_tr_b16 v[10:11], v197 offset:24576
	ds_read_b64_tr_b16 v[12:13], v197 offset:25088
	s_waitcnt lgkmcnt(3)
	v_mfma_f32_32x32x16_bf16 v[80:95], v[2:5], v[140:143], v[80:95]
	v_add_f32_e32 v15, v106, v15
	v_add_f32_e32 v15, v107, v15
	v_add_f32_e32 v15, v108, v15
	v_add_f32_e32 v15, v109, v15
	v_cvt_pk_bf16_f32 v128, v104, v105
	v_cvt_pk_bf16_f32 v129, v106, v107
	ds_read_b64_tr_b16 v[96:97], v197 offset:28672
	ds_read_b64_tr_b16 v[98:99], v197 offset:29184
	s_waitcnt lgkmcnt(4)
	v_mfma_f32_32x32x16_bf16 v[64:79], v[6:9], v[140:143], v[64:79]
	v_add_f32_e32 v2, v110, v15
	v_add_f32_e32 v2, v111, v2
	v_add_f32_e32 v15, 0, v2
	v_cvt_pk_bf16_f32 v130, v108, v109
	v_cvt_pk_bf16_f32 v131, v110, v111
	s_mov_b32 m0, s92
	s_nop 0
	global_load_lds_dwordx4 v200, s[6:7]
	s_nop 0
	v_add_f32_e32 v216, v14, v15
	s_mov_b32 m0, s10
	s_nop 0
	global_load_lds_dwordx4 v201, s[6:7]
	s_add_u32 s0, s4, 0x20000
	s_addc_u32 s1, s5, 0
	s_mov_b32 m0, s93
	s_nop 0
	global_load_lds_dwordx4 v204, s[0:1]
	ds_read_b64_tr_b16 v[6:7], v197 offset:25600
	ds_read_b64_tr_b16 v[8:9], v197 offset:26112
	ds_read_b64_tr_b16 v[2:3], v197 offset:29696
	ds_read_b64_tr_b16 v[4:5], v197 offset:30208
	v_max_f32_e32 v14, v81, v81
	v_max_f32_e32 v15, v80, v80
	v_max_f32_e32 v14, v15, v14
	v_max3_f32 v15, v82, v83, v65
	v_max3_f32 v14, v14, v64, v66
	v_max3_f32 v14, v14, v67, v84
	s_waitcnt lgkmcnt(6)
	v_mfma_f32_32x32x16_bf16 v[32:47], v[164:167], v[10:13], v[32:47]
	v_max3_f32 v10, v15, v86, v87
	v_max3_f32 v11, v14, v85, v68
	v_max3_f32 v10, v10, v70, v71
	v_max3_f32 v11, v11, v69, v88
	v_max3_f32 v10, v10, v90, v91
	v_max3_f32 v11, v11, v89, v72
	v_max3_f32 v10, v10, v74, v75
	s_waitcnt lgkmcnt(4)
	v_mfma_f32_32x32x16_bf16 v[16:31], v[164:167], v[96:99], v[16:31]
	v_max3_f32 v11, v11, v73, v92
	v_max3_f32 v10, v10, v94, v95
	v_max3_f32 v11, v11, v93, v76
	v_max3_f32 v10, v10, v78, v79
	v_max3_f32 v10, v11, v77, v10
	v_cmp_lt_f32_e32 vcc, s85, v10
	s_cmp_lg_u64 vcc, 0
	s_cselect_b64 s[0:1], -1, 0
	s_cbranch_vccnz .LBB0_910
.LBB0_899:
	s_waitcnt lgkmcnt(2)
	v_mfma_f32_32x32x16_bf16 v[32:47], v[136:139], v[6:9], v[32:47]
	ds_read_b64_tr_b16 v[12:13], v197 offset:27136
	ds_read_b64_tr_b16 v[10:11], v197 offset:26624
	ds_read_b128 v[168:171], v206 offset:16384
	v_exp_f32_e32 v80, v80
	v_exp_f32_e32 v81, v81
	v_exp_f32_e32 v82, v82
	v_exp_f32_e32 v83, v83
	s_waitcnt lgkmcnt(3)
	v_mfma_f32_32x32x16_bf16 v[16:31], v[136:139], v[2:5], v[16:31]
	ds_read_b64_tr_b16 v[8:9], v197 offset:31232
	ds_read_b64_tr_b16 v[6:7], v197 offset:30720
	ds_read_b128 v[172:175], v206 offset:24576
	v_exp_f32_e32 v84, v84
	v_exp_f32_e32 v85, v85
	v_exp_f32_e32 v86, v86
	v_exp_f32_e32 v87, v87
	s_waitcnt lgkmcnt(4)
	v_mfma_f32_32x32x16_bf16 v[32:47], v[132:135], v[10:13], v[32:47]
	ds_read_b64_tr_b16 v[4:5], v197 offset:28160
	ds_read_b64_tr_b16 v[2:3], v197 offset:27648
	ds_read_b128 v[180:183], v208 offset:16384
	v_exp_f32_e32 v88, v88
	v_exp_f32_e32 v89, v89
	v_exp_f32_e32 v90, v90
	s_waitcnt lgkmcnt(4)
	v_mfma_f32_32x32x16_bf16 v[16:31], v[132:135], v[6:9], v[16:31]
	ds_read_b64_tr_b16 v[12:13], v197 offset:32256
	ds_read_b64_tr_b16 v[10:11], v197 offset:31744
	ds_read_b128 v[176:179], v208 offset:24576
	v_exp_f32_e32 v91, v91
	v_exp_f32_e32 v92, v92
	v_exp_f32_e32 v93, v93
	s_waitcnt lgkmcnt(4)
	v_mfma_f32_32x32x16_bf16 v[32:47], v[128:131], v[2:5], v[32:47]
	v_exp_f32_e32 v94, v94
	v_exp_f32_e32 v95, v95
	v_exp_f32_e32 v64, v64
	s_waitcnt lgkmcnt(1)
	v_mfma_f32_32x32x16_bf16 v[16:31], v[128:131], v[10:13], v[16:31]
	v_exp_f32_e32 v65, v65
	v_exp_f32_e32 v66, v66
	v_exp_f32_e32 v67, v67
	s_waitcnt vmcnt(3) lgkmcnt(0)
	s_barrier
	s_andn2_b64 vcc, exec, s[0:1]
	s_cbranch_vccnz .LBB0_888
	ds_read_b128 v[2:5], v1 offset:96
	ds_read_b128 v[6:9], v1 offset:64
	ds_read_b128 v[10:13], v1 offset:32
	ds_read_b128 v[96:99], v1
	s_waitcnt lgkmcnt(3)
	v_pk_mul_f32 v[44:45], v[44:45], v[2:3]
	s_waitcnt lgkmcnt(2)
	v_pk_mul_f32 v[40:41], v[40:41], v[6:7]
	s_waitcnt lgkmcnt(1)
	v_pk_mul_f32 v[36:37], v[36:37], v[10:11]
	v_pk_mul_f32 v[46:47], v[46:47], v[4:5]
	v_pk_mul_f32 v[42:43], v[42:43], v[8:9]
	v_pk_mul_f32 v[38:39], v[38:39], v[12:13]
	s_waitcnt lgkmcnt(0)
	v_pk_mul_f32 v[34:35], v[34:35], v[98:99]
	v_pk_mul_f32 v[32:33], v[32:33], v[96:97]
	v_pk_mul_f32 v[28:29], v[28:29], v[2:3]
	v_pk_mul_f32 v[24:25], v[24:25], v[6:7]
	v_pk_mul_f32 v[20:21], v[20:21], v[10:11]
	v_pk_mul_f32 v[30:31], v[30:31], v[4:5]
	v_pk_mul_f32 v[26:27], v[26:27], v[8:9]
	v_pk_mul_f32 v[22:23], v[22:23], v[12:13]
	v_pk_mul_f32 v[18:19], v[18:19], v[98:99]
	v_pk_mul_f32 v[16:17], v[16:17], v[96:97]
	s_branch .LBB0_888

.LBB0_1254:
.LBB0_1255:
	s_cmp_lt_i32 s81, 10
	s_cselect_b64 s[0:1], -1, 0
	s_and_b64 s[6:7], s[0:1], s[2:3]
	s_andn2_b64 vcc, exec, s[6:7]
	s_cbranch_vccnz .LBB0_1275
	s_cmpk_lt_i32 s82, 0x80
	s_cbranch_scc1 .Lp9_nostagger
	s_sleep 127
	s_sleep 127
	s_sleep 127
.Lp9_nostagger:
	s_mov_b64 s[0:1], s[70:71]
	s_load_dwordx2 s[14:15], s[0:1], 0xb8
	s_waitcnt lgkmcnt(0)
	s_add_u32 s0, s14, 0x500000
	s_addc_u32 s1, s15, 0
	s_lshl_b32 s2, s82, 11
	s_and_b32 s3, s80, 0xffffffc0
	s_and_b32 s2, s2, 0x3800
	v_mbcnt_hi_u32_b32 v148, -1, v187
	s_add_i32 s3, s3, s2
	v_add_u32_e32 v48, s3, v148
	v_ashrrev_i32_e32 v49, 31, v48
	v_lshlrev_b64 v[0:1], 6, v[48:49]
	v_lshl_add_u64 v[16:17], s[0:1], 0, v[0:1]
	global_load_dwordx4 v[0:3], v[16:17], off
	global_load_dwordx4 v[4:7], v[16:17], off offset:16
	global_load_dwordx4 v[8:11], v[16:17], off offset:32
	global_load_dwordx4 v[12:15], v[16:17], off offset:48
	v_add_u32_e32 v16, 0x200, v48
	v_ashrrev_i32_e32 v17, 31, v16
	v_lshlrev_b64 v[16:17], 6, v[16:17]
	v_lshl_add_u64 v[32:33], s[0:1], 0, v[16:17]
	global_load_dwordx4 v[16:19], v[32:33], off
	global_load_dwordx4 v[20:23], v[32:33], off offset:16
	global_load_dwordx4 v[24:27], v[32:33], off offset:48
	global_load_dwordx4 v[28:31], v[32:33], off offset:32
	v_add_u32_e32 v32, 0x400, v48
	v_ashrrev_i32_e32 v33, 31, v32
	v_lshlrev_b64 v[32:33], 6, v[32:33]
	v_lshl_add_u64 v[50:51], s[0:1], 0, v[32:33]
	global_load_dwordx4 v[32:35], v[50:51], off
	global_load_dwordx4 v[36:39], v[50:51], off offset:16
	s_mov_b32 s2, 0x358637bd
	v_mov_b64_e32 v[64:65], s[2:3]
	s_lshl_b32 s2, s83, 8
	s_add_i32 s2, s2, 0
	global_load_dwordx4 v[40:43], v[50:51], off offset:48
	global_load_dwordx4 v[44:47], v[50:51], off offset:32
	v_lshl_add_u32 v49, v148, 2, s2
	v_add_u32_e32 v48, 0x600, v48
	v_add_u32_e32 v68, 0x20000, v49
	v_ashrrev_i32_e32 v49, 31, v48
	v_lshlrev_b64 v[48:49], 6, v[48:49]
	v_lshl_add_u64 v[66:67], s[0:1], 0, v[48:49]
	global_load_dwordx4 v[48:51], v[66:67], off offset:16
	global_load_dwordx4 v[52:55], v[66:67], off
	global_load_dwordx4 v[56:59], v[66:67], off offset:48
	global_load_dwordx4 v[60:63], v[66:67], off offset:32
	s_mov_b32 s8, 0x3a800000
	s_mov_b32 s5, 0x800000
	s_movk_i32 s4, 0x400
	s_cmpk_gt_i32 s82, 0x57f
	s_waitcnt vmcnt(0)
	v_mov_b32_e32 v66, v1
	v_mov_b32_e32 v67, v2
	v_mov_b32_e32 v1, v3
	v_mov_b32_e32 v2, v5
	v_mov_b32_e32 v3, v6
	v_mov_b32_e32 v5, v7
	v_add_f32_e32 v6, v8, v9
	v_add_f32_e32 v8, v10, v11
	v_mov_b32_e32 v7, v14
	v_mov_b32_e32 v9, v15
	v_pk_add_f32 v[0:1], v[66:67], v[0:1]
	v_pk_add_f32 v[2:3], v[2:3], v[4:5]
	v_pk_add_f32 v[4:5], v[6:7], v[8:9]
	v_mov_b32_e32 v6, v17
	v_mov_b32_e32 v7, v18
	v_mov_b32_e32 v17, v19
	v_mov_b32_e32 v8, v21
	v_mov_b32_e32 v9, v22
	v_mov_b32_e32 v21, v23
	v_add_f32_e32 v10, v0, v1
	v_pk_add_f32 v[0:1], v[2:3], v[2:3] op_sel:[0,1] op_sel_hi:[1,0]
	v_pk_add_f32 v[2:3], v[6:7], v[16:17]
	v_pk_add_f32 v[6:7], v[8:9], v[20:21]
	v_mov_b32_e32 v11, v12
	v_add_f32_e32 v12, v2, v3
	v_pk_add_f32 v[2:3], v[6:7], v[6:7] op_sel:[0,1] op_sel_hi:[1,0]
	v_add_f32_e32 v14, v28, v29
	v_add_f32_e32 v18, v30, v31
	v_mov_b32_e32 v23, v24
	v_mov_b32_e32 v15, v26
	v_mov_b32_e32 v19, v27
	v_add_f32_e32 v10, 0, v10
	v_mov_b32_e32 v1, v13
	v_add_f32_e32 v22, 0, v12
	v_mov_b32_e32 v3, v25
	v_pk_add_f32 v[8:9], v[14:15], v[18:19]
	v_pk_add_f32 v[0:1], v[10:11], v[0:1]
	v_pk_add_f32 v[2:3], v[22:23], v[2:3]
	v_pk_add_f32 v[0:1], v[0:1], v[4:5]
	v_pk_add_f32 v[2:3], v[2:3], v[8:9]
	v_mov_b32_e32 v5, v0
	v_mov_b32_e32 v4, v2
	v_mov_b32_e32 v0, v3
	v_pk_add_f32 v[0:1], v[4:5], v[0:1]
	v_mov_b32_e32 v26, v33
	v_pk_fma_f32 v[0:1], v[0:1], s[8:9], v[64:65] op_sel_hi:[1,0,0]
	v_mov_b32_e32 v27, v34
	v_mul_f32_e32 v2, 0x4b800000, v1
	v_mul_f32_e32 v3, 0x4b800000, v0
	v_cmp_gt_f32_e32 vcc, s5, v1
	v_cmp_gt_f32_e64 s[2:3], s5, v0
	v_mov_b32_e32 v33, v35
	v_cndmask_b32_e32 v1, v1, v2, vcc
	v_cndmask_b32_e64 v0, v0, v3, s[2:3]
	v_rsq_f32_e32 v2, v1
	v_rsq_f32_e32 v3, v0
	v_pk_add_f32 v[0:1], v[26:27], v[32:33]
	v_add_f32_e32 v6, v46, v47
	v_add_f32_e32 v0, v0, v1
	v_mul_f32_e32 v1, 0x45800000, v2
	v_mul_f32_e32 v4, 0x45800000, v3
	v_cndmask_b32_e32 v10, v2, v1, vcc
	v_cndmask_b32_e64 v11, v3, v4, s[2:3]
	v_mov_b32_e32 v2, v37
	v_mov_b32_e32 v3, v38
	v_mov_b32_e32 v37, v39
	v_pk_add_f32 v[2:3], v[2:3], v[36:37]
	v_add_f32_e32 v0, 0, v0
	v_pk_add_f32 v[2:3], v[2:3], v[2:3] op_sel:[0,1] op_sel_hi:[1,0]
	v_add_f32_e32 v4, v44, v45
	v_mov_b32_e32 v1, v40
	v_mov_b32_e32 v3, v41
	v_mov_b32_e32 v5, v42
	v_mov_b32_e32 v7, v43
	v_pk_add_f32 v[0:1], v[0:1], v[2:3]
	v_pk_add_f32 v[2:3], v[4:5], v[6:7]
	v_mov_b32_e32 v4, v49
	v_pk_add_f32 v[0:1], v[0:1], v[2:3]
	v_mov_b32_e32 v2, v53
	v_mov_b32_e32 v3, v54
	v_mov_b32_e32 v53, v55
	v_mov_b32_e32 v5, v50
	v_mov_b32_e32 v49, v51
	v_pk_add_f32 v[2:3], v[2:3], v[52:53]
	v_pk_add_f32 v[4:5], v[4:5], v[48:49]
	v_add_f32_e32 v2, v2, v3
	v_pk_add_f32 v[4:5], v[4:5], v[4:5] op_sel:[0,1] op_sel_hi:[1,0]
	v_add_f32_e32 v2, 0, v2
	v_add_f32_e32 v6, v60, v61
	v_add_f32_e32 v8, v62, v63
	v_mov_b32_e32 v3, v56
	v_mov_b32_e32 v5, v57
	v_mov_b32_e32 v7, v58
	v_mov_b32_e32 v9, v59
	v_pk_add_f32 v[2:3], v[2:3], v[4:5]
	v_pk_add_f32 v[4:5], v[6:7], v[8:9]
	ds_write2st64_b32 v68, v10, v11 offset1:8
	v_pk_add_f32 v[2:3], v[2:3], v[4:5]
	v_mov_b32_e32 v5, v0
	v_mov_b32_e32 v4, v2
	v_mov_b32_e32 v0, v3
	v_pk_add_f32 v[0:1], v[4:5], v[0:1]
	s_nop 0
	v_pk_fma_f32 v[0:1], v[0:1], s[8:9], v[64:65] op_sel_hi:[1,0,0]
	s_nop 0
	v_mul_f32_e32 v2, 0x4b800000, v1
	v_cmp_gt_f32_e32 vcc, s5, v1
	v_cmp_gt_f32_e64 s[2:3], s5, v0
	s_nop 0
	v_cndmask_b32_e32 v1, v1, v2, vcc
	v_mul_f32_e32 v2, 0x4b800000, v0
	v_rsq_f32_e32 v1, v1
	v_cndmask_b32_e64 v0, v0, v2, s[2:3]
	v_rsq_f32_e32 v0, v0
	v_mul_f32_e32 v2, 0x45800000, v1
	v_cndmask_b32_e32 v1, v1, v2, vcc
	v_mul_f32_e32 v2, 0x45800000, v0
	v_cndmask_b32_e64 v0, v0, v2, s[2:3]
	ds_write2st64_b32 v68, v1, v0 offset0:16 offset1:24
	s_waitcnt lgkmcnt(0)
	s_barrier
	s_cbranch_scc1 .LBB0_1275
	s_add_u32 s33, s14, 0x3000000
	s_addc_u32 s34, s15, 0
	s_add_u32 s35, s14, 0xa00000
	s_addc_u32 s36, s15, 0
	s_lshl_b32 s37, s83, 10
	v_lshl_add_u32 v0, v148, 4, s37
	v_add_u32_e32 v1, 0x2000, v0
	v_ashrrev_i32_e32 v2, 31, v1
	v_lshrrev_b32_e32 v2, 22, v2
	v_add_u32_e32 v2, v1, v2
	v_ashrrev_i32_e32 v149, 10, v2
	v_mul_i32_i24_e32 v2, 0x400, v149
	v_sub_u32_e32 v1, v1, v2
	v_lshrrev_b32_e32 v2, 4, v1
	v_bitop3_b32 v1, v2, v1, 32 bitop3:0x6c
	v_ashrrev_i32_e32 v2, 31, v1
	v_lshrrev_b32_e32 v2, 26, v2
	v_add_u32_e32 v2, v1, v2
	v_ashrrev_i32_e32 v150, 6, v2
	v_lshlrev_b32_e32 v3, 3, v149
	v_and_b32_e32 v2, 0xffc0, v2
	v_and_b32_e32 v3, -16, v3
	v_sub_u32_e32 v1, v1, v2
	v_add_u32_e32 v3, v150, v3
	v_lshrrev_b16_e32 v2, 7, v1
	v_and_b32_e32 v4, 3, v150
	s_mov_b32 s0, 0x7fffffe0
	v_lshrrev_b32_e32 v5, 2, v3
	v_lshlrev_b32_e32 v6, 1, v3
	v_and_b32_e32 v2, 1, v2
	v_and_or_b32 v4, v3, s0, v4
	v_and_b32_e32 v5, 4, v5
	v_and_b32_e32 v6, 24, v6
	v_add_u16_e32 v1, v1, v2
	v_mov_b32_e32 v2, 1
	v_or3_b32 v4, v4, v5, v6
	v_lshlrev_b32_e32 v5, 5, v149
	v_ashrrev_i16_sdwa v1, v2, sext(v1) dst_sel:DWORD dst_unused:UNUSED_PAD src0_sel:DWORD src1_sel:BYTE_0
	v_and_b32_e32 v5, 32, v5
	v_bfe_i32 v151, v1, 0, 16
	v_mul_lo_u32 v4, v4, s4
	v_add_u32_e32 v1, v5, v151
	v_lshlrev_b32_e32 v3, 11, v3
	v_add_lshl_u32 v128, v4, v1, 1
	v_lshl_add_u32 v130, v1, 1, v3
	v_ashrrev_i32_e32 v1, 31, v0
	v_lshrrev_b32_e32 v1, 22, v1
	v_add_u32_e32 v1, v0, v1
	v_ashrrev_i32_e32 v152, 10, v1
	v_mul_i32_i24_e32 v1, 0x400, v152
	v_sub_u32_e32 v0, v0, v1
	v_lshrrev_b32_e32 v1, 4, v0
	v_bitop3_b32 v0, v1, v0, 32 bitop3:0x6c
	v_ashrrev_i32_e32 v1, 31, v0
	v_lshrrev_b32_e32 v1, 26, v1
	v_add_u32_e32 v1, v0, v1
	v_lshlrev_b32_e32 v3, 3, v152
	v_ashrrev_i32_e32 v153, 6, v1
	v_and_b32_e32 v3, -16, v3
	v_add_u32_e32 v3, v153, v3
	v_and_b32_e32 v4, 3, v153
	s_ashr_i32 s38, s82, 31
	v_and_or_b32 v4, v3, s0, v4
	s_lshr_b32 s0, s38, 29
	s_add_i32 s0, s82, s0
	s_ashr_i32 s5, s4, 31
	s_ashr_i32 s1, s0, 3
	s_and_b32 s0, s0, -8
	s_lshr_b32 s3, s80, 8
	s_lshl_b64 s[8:9], s[4:5], 8
	s_lshl_b64 s[10:11], s[4:5], 9
	s_sub_i32 s0, s82, s0
	s_cmp_lt_i32 s0, 0
	s_movk_i32 s39, 0xb1
	s_cselect_b32 s2, s39, 0xb0
	s_mul_i32 s0, s0, s2
	s_add_i32 s0, s0, s1
	s_mul_hi_i32 s1, s0, 0x2e8ba2e9
	s_lshr_b32 s2, s1, 31
	s_ashr_i32 s1, s1, 5
	s_add_i32 s1, s1, s2
	s_lshl_b32 s12, s1, 3
	s_mulk_i32 s1, 0xb0
	s_sub_i32 s0, s0, s1
	s_sext_i32_i16 s1, s0
	s_bfe_u32 s1, s1, 0x3001c
	s_add_i32 s1, s0, s1
	s_sext_i32_i16 s16, s1
	s_and_b32 s1, s1, 0xfff8
	s_sub_i32 s0, s0, s1
	s_lshr_b32 s2, s16, 3
	s_sext_i32_i16 s0, s0
	s_add_i32 s28, s12, s0
	s_bfe_i64 s[0:1], s[2:3], 0x100000
	s_ashr_i32 s16, s16, 3
	s_mul_hi_u32 s0, s10, s16
	s_mul_i32 s1, s10, s1
	v_lshrrev_b32_e32 v5, 2, v3
	v_lshlrev_b32_e32 v6, 1, v3
	v_and_b32_e32 v1, 0xc0, v1
	s_add_i32 s17, s0, s1
	s_lshr_b64 s[0:1], s[4:5], 23
	v_and_b32_e32 v5, 4, v5
	v_and_b32_e32 v6, 24, v6
	v_sub_u32_e32 v0, v0, v1
	s_ashr_i32 s29, s28, 31
	s_mul_i32 s0, s0, s16
	v_or3_b32 v4, v4, v5, v6
	v_lshlrev_b32_e32 v5, 5, v152
	v_ashrrev_i16_sdwa v0, v2, sext(v0) dst_sel:DWORD dst_unused:UNUSED_PAD src0_sel:DWORD src1_sel:BYTE_0
	s_lshl_b64 s[12:13], s[28:29], 19
	s_add_i32 s17, s17, s0
	s_mul_i32 s0, s10, s16
	v_and_b32_e32 v5, 32, v5
	v_bfe_i32 v154, v0, 0, 16
	s_add_u32 s0, s35, s0
	v_mul_lo_u32 v4, v4, s4
	v_add_u32_e32 v0, v5, v154
	s_addc_u32 s1, s36, s17
	s_add_i32 s29, s37, 0
	v_add_lshl_u32 v132, v4, v0, 1
	v_lshlrev_b32_e32 v1, 11, v3
	s_add_i32 m0, s29, 0x10000
	v_lshl_add_u32 v134, v0, 1, v1
	v_pk_mov_b32 v[116:117], 0, 0
	v_pk_mov_b32 v[118:119], 0, 0
	v_pk_mov_b32 v[112:113], 0, 0
	v_pk_mov_b32 v[114:115], 0, 0
	v_pk_mov_b32 v[100:101], 0, 0
	v_pk_mov_b32 v[102:103], 0, 0
	v_pk_mov_b32 v[96:97], 0, 0
	v_pk_mov_b32 v[98:99], 0, 0
	v_pk_mov_b32 v[84:85], 0, 0
	v_pk_mov_b32 v[86:87], 0, 0
	v_pk_mov_b32 v[80:81], 0, 0
	v_pk_mov_b32 v[82:83], 0, 0
	v_pk_mov_b32 v[64:65], 0, 0
	v_pk_mov_b32 v[66:67], 0, 0
	v_pk_mov_b32 v[56:57], 0, 0
	v_pk_mov_b32 v[58:59], 0, 0
	v_pk_mov_b32 v[124:125], 0, 0
	v_pk_mov_b32 v[126:127], 0, 0
	v_pk_mov_b32 v[120:121], 0, 0
	v_pk_mov_b32 v[122:123], 0, 0
	v_pk_mov_b32 v[108:109], 0, 0
	v_pk_mov_b32 v[110:111], 0, 0
	v_pk_mov_b32 v[104:105], 0, 0
	v_pk_mov_b32 v[106:107], 0, 0
	v_pk_mov_b32 v[92:93], 0, 0
	v_pk_mov_b32 v[94:95], 0, 0
	v_pk_mov_b32 v[88:89], 0, 0
	v_pk_mov_b32 v[90:91], 0, 0
	v_pk_mov_b32 v[76:77], 0, 0
	v_pk_mov_b32 v[78:79], 0, 0
	v_pk_mov_b32 v[72:73], 0, 0
	v_pk_mov_b32 v[74:75], 0, 0
	v_pk_mov_b32 v[52:53], 0, 0
	v_pk_mov_b32 v[54:55], 0, 0
	v_pk_mov_b32 v[48:49], 0, 0
	v_pk_mov_b32 v[50:51], 0, 0
	v_pk_mov_b32 v[36:37], 0, 0
	v_pk_mov_b32 v[38:39], 0, 0
	v_pk_mov_b32 v[32:33], 0, 0
	v_pk_mov_b32 v[34:35], 0, 0
	v_pk_mov_b32 v[20:21], 0, 0
	v_pk_mov_b32 v[22:23], 0, 0
	v_pk_mov_b32 v[12:13], 0, 0
	v_pk_mov_b32 v[14:15], 0, 0
	v_pk_mov_b32 v[0:1], 0, 0
	v_pk_mov_b32 v[2:3], 0, 0
	v_pk_mov_b32 v[4:5], 0, 0
	v_pk_mov_b32 v[6:7], 0, 0
	v_pk_mov_b32 v[68:69], 0, 0
	v_pk_mov_b32 v[70:71], 0, 0
	v_pk_mov_b32 v[60:61], 0, 0
	v_pk_mov_b32 v[62:63], 0, 0
	v_pk_mov_b32 v[44:45], 0, 0
	v_pk_mov_b32 v[46:47], 0, 0
	v_pk_mov_b32 v[40:41], 0, 0
	v_pk_mov_b32 v[42:43], 0, 0
	v_pk_mov_b32 v[28:29], 0, 0
	v_pk_mov_b32 v[30:31], 0, 0
	v_pk_mov_b32 v[24:25], 0, 0
	v_pk_mov_b32 v[26:27], 0, 0
	v_pk_mov_b32 v[8:9], 0, 0
	v_pk_mov_b32 v[10:11], 0, 0
	v_pk_mov_b32 v[16:17], 0, 0
	v_pk_mov_b32 v[18:19], 0, 0
	global_load_lds_dwordx4 v132, s[0:1]
	s_add_i32 m0, s29, 0x12000
	s_add_u32 s16, s0, s8
	global_load_lds_dwordx4 v128, s[0:1]
	s_addc_u32 s17, s1, s9
	s_add_i32 m0, s29, 0x14000
	v_mov_b32_e32 v133, 0
	global_load_lds_dwordx4 v132, s[16:17]
	s_add_i32 m0, s29, 0x16000
	s_add_u32 s30, s33, s12
	s_addc_u32 s31, s34, s13
	s_add_i32 s40, s29, 0x2000
	global_load_lds_dwordx4 v128, s[16:17]
	s_mov_b32 m0, s29
	s_add_u32 s12, s30, 0x40000
	global_load_lds_dwordx4 v134, s[30:31]
	s_mov_b32 m0, s40
	s_addc_u32 s13, s31, 0
	s_add_i32 s41, s29, 0x4000
	global_load_lds_dwordx4 v130, s[30:31]
	s_mov_b32 m0, s41
	s_add_i32 s42, s29, 0x6000
	global_load_lds_dwordx4 v134, s[12:13]
	s_mov_b32 m0, s42
	v_mov_b32_e32 v129, v133
	global_load_lds_dwordx4 v130, s[12:13]
	v_mov_b32_e32 v135, v133
	v_mov_b32_e32 v131, v133
	s_cmp_eq_u32 s3, 1
	v_lshl_add_u64 v[144:145], s[0:1], 0, v[132:133]
	v_lshl_add_u64 v[140:141], s[0:1], 0, v[128:129]
	v_lshl_add_u64 v[138:139], s[16:17], 0, v[132:133]
	v_lshl_add_u64 v[136:137], s[16:17], 0, v[128:129]
	v_lshl_add_u64 v[142:143], s[30:31], 0, v[134:135]
	s_cselect_b64 s[12:13], -1, 0
	s_cmp_lg_u32 s3, 1
	v_lshl_add_u64 v[146:147], s[30:31], 0, v[130:131]
	s_cbranch_scc1 .LBB0_1259
	s_barrier
